# speedup vs baseline: 1.0110x; 1.0106x over previous
; __device__ __forceinline__ void finishSM(f32x16& p0, f32x16& p1, float& l_reg, bf16x8& pa0, bf16x8& pa1, bf16x8& pa2, bf16x8& pa3) {
; #pragma unroll
;   for (int r = 0; r < 16; ++r) p1[r] = __builtin_amdgcn_exp2f(p1[r]);
;   float ps = 0;
; #pragma unroll
;   for (int r = 0; r < 16; ++r) ps += p0[r];
; #pragma unroll
;   for (int r = 0; r < 16; ++r) ps += p1[r];
;   { auto rr = __builtin_amdgcn_permlane32_swap(__float_as_uint(ps), __float_as_uint(ps), false, false);
;     ps = __uint_as_float(rr[0]) + __uint_as_float(rr[1]); }
;   l_reg += ps;
; __device__ __forceinline__ void qkt(f32x16& p0, f32x16& p1, const char* Ks, const bf16x8* qr, int r32, int hi, float negM) {
; #pragma unroll
;   for (int r = 0; r < 16; ++r) { p0[r] = negM; p1[r] = negM; }
;   __builtin_amdgcn_s_setprio(1);
;   const char* kn = Ks + r32 * 256; const int xn = r32 & 15;
; #pragma unroll
;   for (int d0 = 0; d0 < 8; ++d0) { const int off = ((d0 * 2 + hi) ^ xn) << 4;
;     bf16x8 b0 = *reinterpret_cast<const bf16x8*>(kn + off);
;     bf16x8 b1 = *reinterpret_cast<const bf16x8*>(kn + 32 * 256 + off);
;     p0 = __builtin_amdgcn_mfma_f32_32x32x16_bf16(b0, qr[d0], p0, 0, 0, 0);
;     p1 = __builtin_amdgcn_mfma_f32_32x32x16_bf16(b1, qr[d0], p1, 0, 0, 0); }
;   const char* kr = Ks + KROPE_OFF + r32 * 128; const int xr = (r32 >> 1) & 7;
; #pragma unroll
;   for (int d0 = 8; d0 < 12; ++d0) { const int off = (((d0 - 8) * 2 + hi) ^ xr) << 4;
;     bf16x8 b0 = *reinterpret_cast<const bf16x8*>(kr + off);
;     bf16x8 b1 = *reinterpret_cast<const bf16x8*>(kr + 32 * 128 + off);
;     p0 = __builtin_amdgcn_mfma_f32_32x32x16_bf16(b0, qr[d0], p0, 0, 0, 0);
;     p1 = __builtin_amdgcn_mfma_f32_32x32x16_bf16(b1, qr[d0], p1, 0, 0, 0); }
;   __builtin_amdgcn_s_setprio(0);
; }
.LBB0_719:
	s_waitcnt vmcnt(0)
	s_waitcnt lgkmcnt(0)
	s_mov_b32 s51, s54
	s_barrier
	s_setprio 1
	v_add_u32_e32 v243, s49, v213
	v_add_u32_e32 v100, v243, v214
	ds_read_b128 v[96:99], v100 offset:16384
	ds_read_b128 v[244:247], v100 offset:24576
	v_add_u32_e32 v248, v243, v215
	s_add_u32 s54, s51, s87
	v_lshl_add_u64 v[188:189], s[26:27], 0, v[184:185]
	v_lshl_add_u64 v[190:191], s[26:27], 0, v[186:187]
	v_lshl_add_u64 v[192:193], s[26:27], 0, v[178:179]
	v_lshl_add_u64 v[194:195], s[26:27], 0, v[182:183]
	v_lshl_add_u64 v[196:197], s[26:27], 0, v[180:181]
	v_exp_f32_e32 v80, v80
	v_add_f32_e32 v252, 0, v240
	v_add_f32_e32 v252, v242, v252
	s_waitcnt lgkmcnt(0)
	v_mfma_f32_32x32x16_bf16 v[112:127], v[96:99], v[128:131], v[0:15]
	v_exp_f32_e32 v81, v81
	v_add_f32_e32 v252, v238, v252
	v_add_f32_e32 v252, v241, v252
	v_mfma_f32_32x32x16_bf16 v[96:111], v[244:247], v[128:131], v[0:15]
	ds_read_b128 v[244:247], v248 offset:16384
	ds_read_b128 v[248:251], v248 offset:24576
	s_add_u32 m0, s54, 0x4000
	v_lshl_add_u64 v[254:255], v[188:189], 0, s[16:17]
	global_load_lds_dwordx4 v[254:255], off
	v_exp_f32_e32 v82, v82
	v_add_f32_e32 v252, v236, v252
	v_add_f32_e32 v252, v239, v252
	s_waitcnt lgkmcnt(0)
	v_mfma_f32_32x32x16_bf16 v[112:127], v[244:247], v[132:135], v[112:127]
	v_exp_f32_e32 v83, v83
	v_add_f32_e32 v252, v235, v252
	v_add_f32_e32 v252, v237, v252
	v_mfma_f32_32x32x16_bf16 v[96:111], v[248:251], v[132:135], v[96:111]
	v_add_u32_e32 v248, v243, v216
	ds_read_b128 v[244:247], v248 offset:16384
	ds_read_b128 v[248:251], v248 offset:24576
	s_add_u32 m0, s54, 0x6000
	v_lshl_add_u64 v[254:255], v[190:191], 0, s[16:17]
	global_load_lds_dwordx4 v[254:255], off
	v_exp_f32_e32 v84, v84
	v_add_f32_e32 v252, v232, v252
	v_add_f32_e32 v252, v234, v252
	s_waitcnt lgkmcnt(0)
	v_mfma_f32_32x32x16_bf16 v[112:127], v[244:247], v[136:139], v[112:127]
	v_exp_f32_e32 v85, v85
	v_add_f32_e32 v252, v230, v252
	v_add_f32_e32 v252, v233, v252
	v_mfma_f32_32x32x16_bf16 v[96:111], v[248:251], v[136:139], v[96:111]
	v_add_u32_e32 v248, v243, v217
	ds_read_b128 v[244:247], v248 offset:16384
	ds_read_b128 v[248:251], v248 offset:24576
	s_add_u32 m0, s54, 0x8000
	v_lshl_add_u64 v[254:255], v[192:193], 0, s[18:19]
	global_load_lds_dwordx4 v[254:255], off
	v_exp_f32_e32 v86, v86
	v_add_f32_e32 v252, v228, v252
	v_add_f32_e32 v252, v231, v252
	s_waitcnt lgkmcnt(0)
	v_mfma_f32_32x32x16_bf16 v[112:127], v[244:247], v[140:143], v[112:127]
	v_exp_f32_e32 v87, v87
	v_add_f32_e32 v252, v227, v252
	v_add_f32_e32 v252, v229, v252
	v_mfma_f32_32x32x16_bf16 v[96:111], v[248:251], v[140:143], v[96:111]
	v_add_u32_e32 v248, v243, v218
	ds_read_b128 v[244:247], v248 offset:16384
	ds_read_b128 v[248:251], v248 offset:24576
	s_mov_b32 m0, s54
	v_lshl_add_u64 v[254:255], v[194:195], 0, s[20:21]
	global_load_lds_dwordx4 v[254:255], off
	v_exp_f32_e32 v88, v88
	v_add_f32_e32 v252, v80, v252
	v_exp_f32_e32 v89, v89
	s_waitcnt lgkmcnt(0)
	v_mfma_f32_32x32x16_bf16 v[112:127], v[244:247], v[144:147], v[112:127]
	v_add_f32_e32 v252, v81, v252
	v_exp_f32_e32 v90, v90
	v_add_f32_e32 v252, v82, v252
	v_mfma_f32_32x32x16_bf16 v[96:111], v[248:251], v[144:147], v[96:111]
	v_add_u32_e32 v248, v243, v219
	ds_read_b128 v[244:247], v248 offset:16384
	ds_read_b128 v[248:251], v248 offset:24576
	s_add_u32 m0, s54, 0x2000
	v_lshl_add_u64 v[254:255], v[196:197], 0, s[20:21]
	global_load_lds_dwordx4 v[254:255], off
	v_exp_f32_e32 v91, v91
	v_add_f32_e32 v252, v83, v252
	v_exp_f32_e32 v92, v92
	s_waitcnt lgkmcnt(0)
	v_mfma_f32_32x32x16_bf16 v[112:127], v[244:247], v[148:151], v[112:127]
	v_add_f32_e32 v252, v84, v252
	v_exp_f32_e32 v93, v93
	v_add_f32_e32 v252, v85, v252
	v_mfma_f32_32x32x16_bf16 v[96:111], v[248:251], v[148:151], v[96:111]
	v_add_u32_e32 v248, v243, v220
	ds_read_b128 v[244:247], v248 offset:16384
	ds_read_b128 v[248:251], v248 offset:24576
	v_add_u32_e32 v243, v243, v221
	v_exp_f32_e32 v94, v94
	v_add_f32_e32 v252, v86, v252
	v_exp_f32_e32 v95, v95
	s_waitcnt lgkmcnt(0)
	v_mfma_f32_32x32x16_bf16 v[112:127], v[244:247], v[152:155], v[112:127]
	v_add_f32_e32 v252, v87, v252
	v_add_f32_e32 v252, v88, v252
	v_add_f32_e32 v252, v89, v252
	v_mfma_f32_32x32x16_bf16 v[96:111], v[248:251], v[152:155], v[96:111]
	ds_read_b128 v[244:247], v243 offset:16384
	ds_read_b128 v[248:251], v243 offset:24576
	v_add_u32_e32 v243, s49, v222
	v_add_f32_e32 v252, v90, v252
	v_add_f32_e32 v252, v91, v252
	v_add_f32_e32 v252, v92, v252
	s_waitcnt lgkmcnt(0)
	v_mfma_f32_32x32x16_bf16 v[112:127], v[244:247], v[156:159], v[112:127]
	v_add_f32_e32 v252, v93, v252
	v_add_f32_e32 v252, v94, v252
	v_add_f32_e32 v252, v95, v252
	v_mfma_f32_32x32x16_bf16 v[96:111], v[248:251], v[156:159], v[96:111]
	v_add_u32_e32 v248, v243, v223
	ds_read_b128 v[244:247], v248 offset:32768
	ds_read_b128 v[248:251], v248 offset:36864
	v_mov_b32_e32 v253, v252
	v_cvt_pk_bf16_f32 v95, v94, v95
	v_cvt_pk_bf16_f32 v94, v92, v93
	s_waitcnt lgkmcnt(0)
	v_mfma_f32_32x32x16_bf16 v[112:127], v[244:247], v[164:167], v[112:127]
	v_permlane32_swap_b32_e32 v252, v253
	v_cvt_pk_bf16_f32 v93, v90, v91
	v_cvt_pk_bf16_f32 v92, v88, v89
	v_mfma_f32_32x32x16_bf16 v[96:111], v[248:251], v[164:167], v[96:111]
	v_add_u32_e32 v248, v243, v224
	ds_read_b128 v[244:247], v248 offset:32768
	ds_read_b128 v[248:251], v248 offset:36864
	v_add_f32_e32 v252, v252, v253
	v_cvt_pk_bf16_f32 v91, v86, v87
	v_add_f32_e32 v176, v176, v252
	s_waitcnt lgkmcnt(0)
; #define SBAR() __builtin_amdgcn_sched_barrier(0)
; __device__ __forceinline__ void finishSM(f32x16& p0, f32x16& p1, float& l_reg, bf16x8& pa0, bf16x8& pa1, bf16x8& pa2, bf16x8& pa3) {
;     ...
;   PK4(p0, 0, pa0); PK4(p0, 8, pa1); PK4(p1, 0, pa2); PK4(p1, 8, pa3);
; template <int OFF> __device__ __forceinline__ s16x4 tr_read(int vb) {
;   s16x4 r; asm volatile("ds_read_b64_tr_b16 %0, %1 offset:%2" : "=&v"(r) : "v"(vb), "i"(OFF) : "memory"); return r;
; }
; template <int D0> __device__ __forceinline__ void pv_one(f32x16& od, int vb, bf16x8 pa0, bf16x8 pa1, bf16x8 pa2, bf16x8 pa3) {
;   const s16x4 l0 = tr_read<v_rd_off(D0, 0, 0)>(vb), h0 = tr_read<v_rd_off(D0, 0, 1)>(vb), l1 = tr_read<v_rd_off(D0, 1, 0)>(vb), h1 = tr_read<v_rd_off(D0, 1, 1)>(vb);
;   const s16x4 l2 = tr_read<v_rd_off(D0, 2, 0)>(vb), h2 = tr_read<v_rd_off(D0, 2, 1)>(vb), l3 = tr_read<v_rd_off(D0, 3, 0)>(vb), h3 = tr_read<v_rd_off(D0, 3, 1)>(vb);
;   asm volatile("s_waitcnt lgkmcnt(0)" ::: "memory"); SBAR();
;     ...
;   od = __builtin_amdgcn_mfma_f32_32x32x16_bf16(pa0, PK(l0, h0), od, 0, 0, 0);
;   od = __builtin_amdgcn_mfma_f32_32x32x16_bf16(pa1, PK(l1, h1), od, 0, 0, 0);
;   od = __builtin_amdgcn_mfma_f32_32x32x16_bf16(pa2, PK(l2, h2), od, 0, 0, 0);
;   od = __builtin_amdgcn_mfma_f32_32x32x16_bf16(pa3, PK(l3, h3), od, 0, 0, 0);
;     ...
; }
; __device__ __forceinline__ void pv_d0(f32x16* o, int vb, bf16x8 pa0, bf16x8 pa1, bf16x8 pa2, bf16x8 pa3) {
;   pv_one<0>(o[0], vb, pa0, pa1, pa2, pa3); pv_one<1>(o[1], vb, pa0, pa1, pa2, pa3); pv_one<2>(o[2], vb, pa0, pa1, pa2, pa3); pv_one<3>(o[3], vb, pa0, pa1, pa2, pa3);
	v_mfma_f32_32x32x16_bf16 v[112:127], v[244:247], v[172:175], v[112:127]
	v_cvt_pk_bf16_f32 v90, v84, v85
	v_cvt_pk_bf16_f32 v89, v82, v83
	v_cvt_pk_bf16_f32 v88, v80, v81
	v_mfma_f32_32x32x16_bf16 v[96:111], v[248:251], v[172:175], v[96:111]
	v_add_u32_e32 v248, v243, v225
	ds_read_b128 v[244:247], v248 offset:32768
	ds_read_b128 v[248:251], v248 offset:36864
	v_add_u32_e32 v243, v243, v226
	v_cvt_pk_bf16_f32 v80, v240, v242
	v_cvt_pk_bf16_f32 v81, v238, v241
	v_cvt_pk_bf16_f32 v82, v236, v239
	s_waitcnt lgkmcnt(0)
	v_mfma_f32_32x32x16_bf16 v[112:127], v[244:247], v[160:163], v[112:127]
	v_cvt_pk_bf16_f32 v83, v235, v237
	v_cvt_pk_bf16_f32 v84, v232, v234
	v_cvt_pk_bf16_f32 v85, v230, v233
	v_mfma_f32_32x32x16_bf16 v[96:111], v[248:251], v[160:163], v[96:111]
	ds_read_b128 v[244:247], v243 offset:32768
	ds_read_b128 v[248:251], v243 offset:36864
	v_cvt_pk_bf16_f32 v86, v228, v231
	v_cvt_pk_bf16_f32 v87, v227, v229
	v_permlane32_swap_b32_e32 v88, v90
	s_waitcnt lgkmcnt(0)
	v_add_u32_e32 v198, s50, v212
	ds_read_b64_tr_b16 v[228:229], v198 offset:0
	ds_read_b64_tr_b16 v[230:231], v198 offset:0x800
	ds_read_b64_tr_b16 v[232:233], v198 offset:0x1000
	ds_read_b64_tr_b16 v[234:235], v198 offset:0x1800
	ds_read_b64_tr_b16 v[236:237], v198 offset:0x2000
	ds_read_b64_tr_b16 v[238:239], v198 offset:0x2800
	ds_read_b64_tr_b16 v[240:241], v198 offset:0x3000
	ds_read_b64_tr_b16 v[242:243], v198 offset:0x3800
	v_mfma_f32_32x32x16_bf16 v[112:127], v[244:247], v[168:171], v[112:127]
	v_permlane32_swap_b32_e32 v89, v91
	v_permlane32_swap_b32_e32 v92, v94
	v_permlane32_swap_b32_e32 v93, v95
	v_mfma_f32_32x32x16_bf16 v[96:111], v[248:251], v[168:171], v[96:111]
	s_setprio 0
	v_permlane32_swap_b32_e32 v80, v82
	v_permlane32_swap_b32_e32 v81, v83
	v_permlane32_swap_b32_e32 v84, v86
	v_permlane32_swap_b32_e32 v85, v87
	s_waitcnt lgkmcnt(0)
	s_nop 0
	v_mfma_f32_32x32x16_bf16 v[64:79], v[80:83], v[228:231], v[64:79]
	ds_read_b64_tr_b16 v[228:229], v198 offset:0x200
	ds_read_b64_tr_b16 v[230:231], v198 offset:0xa00
	v_mfma_f32_32x32x16_bf16 v[64:79], v[84:87], v[232:235], v[64:79]
	ds_read_b64_tr_b16 v[232:233], v198 offset:0x1200
	ds_read_b64_tr_b16 v[234:235], v198 offset:0x1a00
	v_mfma_f32_32x32x16_bf16 v[64:79], v[88:91], v[236:239], v[64:79]
	ds_read_b64_tr_b16 v[236:237], v198 offset:0x2200
	ds_read_b64_tr_b16 v[238:239], v198 offset:0x2a00
	ds_read_b64_tr_b16 v[244:245], v198 offset:0x3200
	ds_read_b64_tr_b16 v[246:247], v198 offset:0x3a00
	s_waitcnt lgkmcnt(0)
	v_mfma_f32_32x32x16_bf16 v[64:79], v[92:95], v[240:243], v[64:79]
	v_mfma_f32_32x32x16_bf16 v[48:63], v[80:83], v[228:231], v[48:63]
	ds_read_b64_tr_b16 v[228:229], v198 offset:0x400
	ds_read_b64_tr_b16 v[230:231], v198 offset:0xc00
	v_mfma_f32_32x32x16_bf16 v[48:63], v[84:87], v[232:235], v[48:63]
	ds_read_b64_tr_b16 v[232:233], v198 offset:0x1400
	ds_read_b64_tr_b16 v[234:235], v198 offset:0x1c00
	v_mfma_f32_32x32x16_bf16 v[48:63], v[88:91], v[236:239], v[48:63]
	ds_read_b64_tr_b16 v[236:237], v198 offset:0x2400
	ds_read_b64_tr_b16 v[238:239], v198 offset:0x2c00
	ds_read_b64_tr_b16 v[240:241], v198 offset:0x3400
	ds_read_b64_tr_b16 v[242:243], v198 offset:0x3c00
	s_waitcnt lgkmcnt(0)
	v_mfma_f32_32x32x16_bf16 v[48:63], v[92:95], v[244:247], v[48:63]
	v_mfma_f32_32x32x16_bf16 v[32:47], v[80:83], v[228:231], v[32:47]
	ds_read_b64_tr_b16 v[228:229], v198 offset:0x600
	ds_read_b64_tr_b16 v[230:231], v198 offset:0xe00
	v_mfma_f32_32x32x16_bf16 v[32:47], v[84:87], v[232:235], v[32:47]
	ds_read_b64_tr_b16 v[232:233], v198 offset:0x1600
	ds_read_b64_tr_b16 v[234:235], v198 offset:0x1e00
	v_mfma_f32_32x32x16_bf16 v[32:47], v[88:91], v[236:239], v[32:47]
	ds_read_b64_tr_b16 v[236:237], v198 offset:0x2600
	ds_read_b64_tr_b16 v[238:239], v198 offset:0x2e00
	ds_read_b64_tr_b16 v[244:245], v198 offset:0x3600
	ds_read_b64_tr_b16 v[246:247], v198 offset:0x3e00
	s_waitcnt lgkmcnt(0)
	v_mfma_f32_32x32x16_bf16 v[32:47], v[92:95], v[240:243], v[32:47]
	v_mfma_f32_32x32x16_bf16 v[16:31], v[80:83], v[228:231], v[16:31]
	v_exp_f32_e32 v227, v114
	v_exp_f32_e32 v228, v115
	v_exp_f32_e32 v229, v116
	v_exp_f32_e32 v230, v117
	v_exp_f32_e32 v231, v118
	v_exp_f32_e32 v240, v127
	s_waitcnt vmcnt(0)
	v_mfma_f32_32x32x16_bf16 v[16:31], v[84:87], v[232:235], v[16:31]
	v_exp_f32_e32 v232, v119
	v_exp_f32_e32 v233, v120
	v_exp_f32_e32 v234, v121
	v_exp_f32_e32 v235, v122
	s_waitcnt lgkmcnt(0)
	v_exp_f32_e32 v198, v112
	v_exp_f32_e32 v199, v113
	v_mfma_f32_32x32x16_bf16 v[16:31], v[88:91], v[236:239], v[16:31]
	v_exp_f32_e32 v236, v123
	v_exp_f32_e32 v237, v124
	v_exp_f32_e32 v238, v125
	v_exp_f32_e32 v239, v126
	s_barrier
; __device__ __forceinline__ void finishSM(f32x16& p0, f32x16& p1, float& l_reg, bf16x8& pa0, bf16x8& pa1, bf16x8& pa2, bf16x8& pa3) {
; #pragma unroll
;   for (int r = 0; r < 16; ++r) p1[r] = __builtin_amdgcn_exp2f(p1[r]);
;   float ps = 0;
; #pragma unroll
;   for (int r = 0; r < 16; ++r) ps += p0[r];
; #pragma unroll
;   for (int r = 0; r < 16; ++r) ps += p1[r];
;   { auto rr = __builtin_amdgcn_permlane32_swap(__float_as_uint(ps), __float_as_uint(ps), false, false);
;     ps = __uint_as_float(rr[0]) + __uint_as_float(rr[1]); }
;   l_reg += ps;
; __device__ __forceinline__ void qkt(f32x16& p0, f32x16& p1, const char* Ks, const bf16x8* qr, int r32, int hi, float negM) {
; #pragma unroll
;   for (int r = 0; r < 16; ++r) { p0[r] = negM; p1[r] = negM; }
;   __builtin_amdgcn_s_setprio(1);
;   const char* kn = Ks + r32 * 256; const int xn = r32 & 15;
; #pragma unroll
;   for (int d0 = 0; d0 < 8; ++d0) { const int off = ((d0 * 2 + hi) ^ xn) << 4;
;     bf16x8 b0 = *reinterpret_cast<const bf16x8*>(kn + off);
;     bf16x8 b1 = *reinterpret_cast<const bf16x8*>(kn + 32 * 256 + off);
;     p0 = __builtin_amdgcn_mfma_f32_32x32x16_bf16(b0, qr[d0], p0, 0, 0, 0);
;     p1 = __builtin_amdgcn_mfma_f32_32x32x16_bf16(b1, qr[d0], p1, 0, 0, 0); }
;   const char* kr = Ks + KROPE_OFF + r32 * 128; const int xr = (r32 >> 1) & 7;
; #pragma unroll
;   for (int d0 = 8; d0 < 12; ++d0) { const int off = (((d0 - 8) * 2 + hi) ^ xr) << 4;
;     bf16x8 b0 = *reinterpret_cast<const bf16x8*>(kr + off);
;     bf16x8 b1 = *reinterpret_cast<const bf16x8*>(kr + 32 * 128 + off);
;     p0 = __builtin_amdgcn_mfma_f32_32x32x16_bf16(b0, qr[d0], p0, 0, 0, 0);
;     p1 = __builtin_amdgcn_mfma_f32_32x32x16_bf16(b1, qr[d0], p1, 0, 0, 0); }
;   __builtin_amdgcn_s_setprio(0);
; }
	v_mfma_f32_32x32x16_bf16 v[16:31], v[92:95], v[244:247], v[16:31]
	s_setprio 1
	v_add_u32_e32 v243, s51, v213
	v_add_u32_e32 v84, v243, v214
	ds_read_b128 v[80:83], v84 offset:16384
	ds_read_b128 v[244:247], v84 offset:24576
	v_add_u32_e32 v248, v243, v215
	s_add_u32 s54, s50, s87
	v_exp_f32_e32 v96, v96
	v_add_f32_e32 v252, 0, v198
	v_add_f32_e32 v252, v199, v252
	s_waitcnt lgkmcnt(0)
	v_mfma_f32_32x32x16_bf16 v[112:127], v[80:83], v[128:131], v[0:15]
	v_exp_f32_e32 v97, v97
	v_add_f32_e32 v252, v227, v252
	v_add_f32_e32 v252, v228, v252
	v_mfma_f32_32x32x16_bf16 v[80:95], v[244:247], v[128:131], v[0:15]
	ds_read_b128 v[244:247], v248 offset:16384
	ds_read_b128 v[248:251], v248 offset:24576
	s_add_u32 m0, s54, 0x4000
	v_lshl_add_u64 v[254:255], v[188:189], 0, s[22:23]
	global_load_lds_dwordx4 v[254:255], off
	v_exp_f32_e32 v98, v98
	v_add_f32_e32 v252, v229, v252
	v_add_f32_e32 v252, v230, v252
	s_waitcnt lgkmcnt(0)
	v_mfma_f32_32x32x16_bf16 v[80:95], v[248:251], v[132:135], v[80:95]
	v_exp_f32_e32 v99, v99
	v_add_f32_e32 v252, v231, v252
	v_add_f32_e32 v252, v232, v252
	v_add_u32_e32 v248, v243, v216
	v_mfma_f32_32x32x16_bf16 v[112:127], v[244:247], v[132:135], v[112:127]
	ds_read_b128 v[244:247], v248 offset:16384
	ds_read_b128 v[248:251], v248 offset:24576
	s_add_u32 m0, s54, 0x6000
	v_lshl_add_u64 v[254:255], v[190:191], 0, s[22:23]
	global_load_lds_dwordx4 v[254:255], off
	v_exp_f32_e32 v100, v100
	v_add_f32_e32 v252, v233, v252
	v_add_f32_e32 v252, v234, v252
	s_waitcnt lgkmcnt(0)
	v_mfma_f32_32x32x16_bf16 v[80:95], v[248:251], v[136:139], v[80:95]
	v_exp_f32_e32 v101, v101
	v_add_f32_e32 v252, v235, v252
	v_add_f32_e32 v252, v236, v252
	v_add_u32_e32 v248, v243, v217
	v_mfma_f32_32x32x16_bf16 v[112:127], v[244:247], v[136:139], v[112:127]
	ds_read_b128 v[244:247], v248 offset:16384
	ds_read_b128 v[248:251], v248 offset:24576
	s_add_u32 m0, s54, 0x8000
	v_lshl_add_u64 v[254:255], v[192:193], 0, s[40:41]
	global_load_lds_dwordx4 v[254:255], off
	v_exp_f32_e32 v102, v102
	v_add_f32_e32 v252, v237, v252
	v_add_f32_e32 v252, v238, v252
	s_waitcnt lgkmcnt(0)
	v_mfma_f32_32x32x16_bf16 v[80:95], v[248:251], v[140:143], v[80:95]
	v_exp_f32_e32 v103, v103
	v_add_f32_e32 v252, v239, v252
	v_add_f32_e32 v252, v240, v252
	v_add_u32_e32 v248, v243, v218
	v_mfma_f32_32x32x16_bf16 v[112:127], v[244:247], v[140:143], v[112:127]
	ds_read_b128 v[244:247], v248 offset:16384
	ds_read_b128 v[248:251], v248 offset:24576
	s_mov_b32 m0, s54
	v_lshl_add_u64 v[254:255], v[194:195], 0, s[42:43]
	global_load_lds_dwordx4 v[254:255], off
	v_exp_f32_e32 v104, v104
	v_add_f32_e32 v252, v96, v252
	v_exp_f32_e32 v105, v105
	s_waitcnt lgkmcnt(0)
	v_mfma_f32_32x32x16_bf16 v[80:95], v[248:251], v[144:147], v[80:95]
	v_add_f32_e32 v252, v97, v252
	v_exp_f32_e32 v106, v106
	v_add_f32_e32 v252, v98, v252
	v_add_u32_e32 v248, v243, v219
	v_mfma_f32_32x32x16_bf16 v[112:127], v[244:247], v[144:147], v[112:127]
	ds_read_b128 v[244:247], v248 offset:16384
	ds_read_b128 v[248:251], v248 offset:24576
	s_add_u32 m0, s54, 0x2000
	v_lshl_add_u64 v[254:255], v[196:197], 0, s[42:43]
	global_load_lds_dwordx4 v[254:255], off
	v_exp_f32_e32 v107, v107
	v_add_f32_e32 v252, v99, v252
	v_exp_f32_e32 v108, v108
	s_waitcnt lgkmcnt(0)
	v_mfma_f32_32x32x16_bf16 v[80:95], v[248:251], v[148:151], v[80:95]
	v_add_f32_e32 v252, v100, v252
	v_exp_f32_e32 v109, v109
	v_add_f32_e32 v252, v101, v252
	v_add_u32_e32 v248, v243, v220
	v_mfma_f32_32x32x16_bf16 v[112:127], v[244:247], v[148:151], v[112:127]
	ds_read_b128 v[244:247], v248 offset:16384
	ds_read_b128 v[248:251], v248 offset:24576
	v_exp_f32_e32 v110, v110
	v_add_f32_e32 v252, v102, v252
	v_exp_f32_e32 v111, v111
	s_waitcnt lgkmcnt(0)
	v_mfma_f32_32x32x16_bf16 v[80:95], v[248:251], v[152:155], v[80:95]
	v_add_f32_e32 v252, v103, v252
	v_add_f32_e32 v252, v104, v252
	v_add_f32_e32 v252, v105, v252
	v_add_u32_e32 v248, v243, v221
	v_add_u32_e32 v243, s51, v222
	v_mfma_f32_32x32x16_bf16 v[112:127], v[244:247], v[152:155], v[112:127]
	ds_read_b128 v[244:247], v248 offset:16384
	ds_read_b128 v[248:251], v248 offset:24576
	v_add_f32_e32 v252, v106, v252
	v_add_f32_e32 v252, v107, v252
	v_add_f32_e32 v252, v108, v252
	s_waitcnt lgkmcnt(0)
	v_mfma_f32_32x32x16_bf16 v[80:95], v[248:251], v[156:159], v[80:95]
	v_add_f32_e32 v252, v109, v252
	v_add_f32_e32 v252, v110, v252
	v_add_f32_e32 v252, v111, v252
	v_add_u32_e32 v248, v243, v223
	v_mfma_f32_32x32x16_bf16 v[112:127], v[244:247], v[156:159], v[112:127]
	ds_read_b128 v[244:247], v248 offset:32768
	ds_read_b128 v[248:251], v248 offset:36864
	v_mov_b32_e32 v253, v252
	v_cvt_pk_bf16_f32 v111, v110, v111
	v_cvt_pk_bf16_f32 v110, v108, v109
	s_waitcnt lgkmcnt(0)
	v_mfma_f32_32x32x16_bf16 v[80:95], v[248:251], v[164:167], v[80:95]
	v_permlane32_swap_b32_e32 v252, v253
	v_cvt_pk_bf16_f32 v109, v106, v107
	v_cvt_pk_bf16_f32 v108, v104, v105
	v_add_u32_e32 v248, v243, v224
	v_mfma_f32_32x32x16_bf16 v[112:127], v[244:247], v[164:167], v[112:127]
	ds_read_b128 v[244:247], v248 offset:32768
	ds_read_b128 v[248:251], v248 offset:36864
	v_add_f32_e32 v252, v252, v253
	v_cvt_pk_bf16_f32 v107, v102, v103
	v_add_f32_e32 v176, v176, v252
	s_waitcnt lgkmcnt(0)
	v_mfma_f32_32x32x16_bf16 v[80:95], v[248:251], v[172:175], v[80:95]
	v_cvt_pk_bf16_f32 v106, v100, v101
	v_cvt_pk_bf16_f32 v105, v98, v99
	v_cvt_pk_bf16_f32 v104, v96, v97
	v_add_u32_e32 v248, v243, v225
	v_mfma_f32_32x32x16_bf16 v[112:127], v[244:247], v[172:175], v[112:127]
	ds_read_b128 v[244:247], v248 offset:32768
	ds_read_b128 v[248:251], v248 offset:36864
	v_cvt_pk_bf16_f32 v96, v198, v199
	v_cvt_pk_bf16_f32 v97, v227, v228
	v_cvt_pk_bf16_f32 v98, v229, v230
	s_waitcnt lgkmcnt(0)
; #define SBAR() __builtin_amdgcn_sched_barrier(0)
; __device__ __forceinline__ void finishSM(f32x16& p0, f32x16& p1, float& l_reg, bf16x8& pa0, bf16x8& pa1, bf16x8& pa2, bf16x8& pa3) {
;     ...
;   PK4(p0, 0, pa0); PK4(p0, 8, pa1); PK4(p1, 0, pa2); PK4(p1, 8, pa3);
; template <int OFF> __device__ __forceinline__ s16x4 tr_read(int vb) {
;   s16x4 r; asm volatile("ds_read_b64_tr_b16 %0, %1 offset:%2" : "=&v"(r) : "v"(vb), "i"(OFF) : "memory"); return r;
; }
; template <int D0> __device__ __forceinline__ void pv_one(f32x16& od, int vb, bf16x8 pa0, bf16x8 pa1, bf16x8 pa2, bf16x8 pa3) {
;   const s16x4 l0 = tr_read<v_rd_off(D0, 0, 0)>(vb), h0 = tr_read<v_rd_off(D0, 0, 1)>(vb), l1 = tr_read<v_rd_off(D0, 1, 0)>(vb), h1 = tr_read<v_rd_off(D0, 1, 1)>(vb);
;   const s16x4 l2 = tr_read<v_rd_off(D0, 2, 0)>(vb), h2 = tr_read<v_rd_off(D0, 2, 1)>(vb), l3 = tr_read<v_rd_off(D0, 3, 0)>(vb), h3 = tr_read<v_rd_off(D0, 3, 1)>(vb);
;   asm volatile("s_waitcnt lgkmcnt(0)" ::: "memory"); SBAR();
;     ...
;   od = __builtin_amdgcn_mfma_f32_32x32x16_bf16(pa0, PK(l0, h0), od, 0, 0, 0);
;   od = __builtin_amdgcn_mfma_f32_32x32x16_bf16(pa1, PK(l1, h1), od, 0, 0, 0);
;   od = __builtin_amdgcn_mfma_f32_32x32x16_bf16(pa2, PK(l2, h2), od, 0, 0, 0);
;   od = __builtin_amdgcn_mfma_f32_32x32x16_bf16(pa3, PK(l3, h3), od, 0, 0, 0);
;     ...
; }
; __device__ __forceinline__ void pv_d0(f32x16* o, int vb, bf16x8 pa0, bf16x8 pa1, bf16x8 pa2, bf16x8 pa3) {
;   pv_one<0>(o[0], vb, pa0, pa1, pa2, pa3); pv_one<1>(o[1], vb, pa0, pa1, pa2, pa3); pv_one<2>(o[2], vb, pa0, pa1, pa2, pa3); pv_one<3>(o[3], vb, pa0, pa1, pa2, pa3);
	v_mfma_f32_32x32x16_bf16 v[80:95], v[248:251], v[160:163], v[80:95]
	v_cvt_pk_bf16_f32 v99, v231, v232
	v_cvt_pk_bf16_f32 v100, v233, v234
	v_cvt_pk_bf16_f32 v101, v235, v236
	v_add_u32_e32 v248, v243, v226
	v_mfma_f32_32x32x16_bf16 v[112:127], v[244:247], v[160:163], v[112:127]
	ds_read_b128 v[244:247], v248 offset:32768
	ds_read_b128 v[248:251], v248 offset:36864
	v_cvt_pk_bf16_f32 v102, v237, v238
	v_cvt_pk_bf16_f32 v103, v239, v240
	v_permlane32_swap_b32_e32 v104, v106
	s_waitcnt lgkmcnt(0)
	v_add_u32_e32 v196, s49, v212
	ds_read_b64_tr_b16 v[188:189], v196 offset:0
	ds_read_b64_tr_b16 v[190:191], v196 offset:0x800
	ds_read_b64_tr_b16 v[192:193], v196 offset:0x1000
	ds_read_b64_tr_b16 v[194:195], v196 offset:0x1800
	ds_read_b64_tr_b16 v[228:229], v196 offset:0x2000
	ds_read_b64_tr_b16 v[230:231], v196 offset:0x2800
	ds_read_b64_tr_b16 v[232:233], v196 offset:0x3000
	ds_read_b64_tr_b16 v[234:235], v196 offset:0x3800
	v_mfma_f32_32x32x16_bf16 v[80:95], v[248:251], v[168:171], v[80:95]
	v_permlane32_swap_b32_e32 v105, v107
	v_permlane32_swap_b32_e32 v108, v110
	v_permlane32_swap_b32_e32 v109, v111
	v_mfma_f32_32x32x16_bf16 v[112:127], v[244:247], v[168:171], v[112:127]
	s_setprio 0
	v_permlane32_swap_b32_e32 v96, v98
	v_permlane32_swap_b32_e32 v97, v99
	v_permlane32_swap_b32_e32 v100, v102
	v_permlane32_swap_b32_e32 v101, v103
	s_waitcnt lgkmcnt(0)
	s_nop 0
	v_mfma_f32_32x32x16_bf16 v[64:79], v[96:99], v[188:191], v[64:79]
	ds_read_b64_tr_b16 v[188:189], v196 offset:0x200
	ds_read_b64_tr_b16 v[190:191], v196 offset:0xa00
	v_mfma_f32_32x32x16_bf16 v[64:79], v[100:103], v[192:195], v[64:79]
	ds_read_b64_tr_b16 v[192:193], v196 offset:0x1200
	ds_read_b64_tr_b16 v[194:195], v196 offset:0x1a00
	v_mfma_f32_32x32x16_bf16 v[64:79], v[104:107], v[228:231], v[64:79]
	ds_read_b64_tr_b16 v[228:229], v196 offset:0x2200
	ds_read_b64_tr_b16 v[230:231], v196 offset:0x2a00
	ds_read_b64_tr_b16 v[236:237], v196 offset:0x3200
	ds_read_b64_tr_b16 v[238:239], v196 offset:0x3a00
	s_waitcnt lgkmcnt(0)
	v_mfma_f32_32x32x16_bf16 v[64:79], v[108:111], v[232:235], v[64:79]
	v_mfma_f32_32x32x16_bf16 v[48:63], v[96:99], v[188:191], v[48:63]
	ds_read_b64_tr_b16 v[188:189], v196 offset:0x400
	ds_read_b64_tr_b16 v[190:191], v196 offset:0xc00
	v_mfma_f32_32x32x16_bf16 v[48:63], v[100:103], v[192:195], v[48:63]
	ds_read_b64_tr_b16 v[192:193], v196 offset:0x1400
	ds_read_b64_tr_b16 v[194:195], v196 offset:0x1c00
	v_mfma_f32_32x32x16_bf16 v[48:63], v[104:107], v[228:231], v[48:63]
	ds_read_b64_tr_b16 v[228:229], v196 offset:0x2400
	ds_read_b64_tr_b16 v[230:231], v196 offset:0x2c00
	ds_read_b64_tr_b16 v[232:233], v196 offset:0x3400
	ds_read_b64_tr_b16 v[234:235], v196 offset:0x3c00
	s_waitcnt lgkmcnt(0)
	v_mfma_f32_32x32x16_bf16 v[48:63], v[108:111], v[236:239], v[48:63]
	v_mfma_f32_32x32x16_bf16 v[32:47], v[96:99], v[188:191], v[32:47]
	ds_read_b64_tr_b16 v[188:189], v196 offset:0x600
	ds_read_b64_tr_b16 v[190:191], v196 offset:0xe00
	v_mfma_f32_32x32x16_bf16 v[32:47], v[100:103], v[192:195], v[32:47]
	ds_read_b64_tr_b16 v[192:193], v196 offset:0x1600
	ds_read_b64_tr_b16 v[194:195], v196 offset:0x1e00
	ds_read_b64_tr_b16 v[244:245], v196 offset:0x2600
	ds_read_b64_tr_b16 v[246:247], v196 offset:0x2e00
	ds_read_b64_tr_b16 v[248:249], v196 offset:0x3600
	ds_read_b64_tr_b16 v[250:251], v196 offset:0x3e00
	s_waitcnt lgkmcnt(0)
	v_mfma_f32_32x32x16_bf16 v[32:47], v[104:107], v[228:231], v[32:47]
	v_mfma_f32_32x32x16_bf16 v[32:47], v[108:111], v[232:235], v[32:47]
	v_mfma_f32_32x32x16_bf16 v[16:31], v[96:99], v[188:191], v[16:31]
	v_exp_f32_e32 v240, v112
	v_exp_f32_e32 v242, v113
	v_exp_f32_e32 v238, v114
	v_exp_f32_e32 v241, v115
	v_exp_f32_e32 v236, v116
	v_exp_f32_e32 v239, v117
	v_exp_f32_e32 v235, v118
	v_mfma_f32_32x32x16_bf16 v[16:31], v[100:103], v[192:195], v[16:31]
	v_exp_f32_e32 v237, v119
	v_exp_f32_e32 v232, v120
	v_exp_f32_e32 v234, v121
	v_exp_f32_e32 v230, v122
	v_exp_f32_e32 v233, v123
	v_exp_f32_e32 v228, v124
	v_exp_f32_e32 v231, v125
	v_mfma_f32_32x32x16_bf16 v[16:31], v[104:107], v[244:247], v[16:31]
	v_exp_f32_e32 v227, v126
	v_exp_f32_e32 v229, v127
	s_add_i32 s48, s48, 2
	v_lshl_add_u64 v[178:179], v[178:179], 0, s[44:45]
	v_lshl_add_u64 v[180:181], v[180:181], 0, s[46:47]
	v_lshl_add_u64 v[182:183], v[182:183], 0, s[46:47]
	v_lshl_add_u64 v[184:185], v[184:185], 0, s[46:47]
	v_mfma_f32_32x32x16_bf16 v[16:31], v[108:111], v[248:251], v[16:31]
	v_lshl_add_u64 v[186:187], v[186:187], 0, s[46:47]
	s_mov_b32 s54, s49
	s_mov_b32 s49, s50
	s_cmp_gt_u32 s48, 28
	s_mov_b32 s50, s51
	s_cbranch_scc0 .LBB0_719
	s_waitcnt vmcnt(0)
	s_waitcnt lgkmcnt(0)
	v_and_b32_e32 v96, 0x3fffffc0, v210
	v_mov_b32_e32 v97, 0x1e000
	v_lshl_add_u32 v178, v96, 2, v97
	s_barrier
; __device__ __forceinline__ void finishSM(f32x16& p0, f32x16& p1, float& l_reg, bf16x8& pa0, bf16x8& pa1, bf16x8& pa2, bf16x8& pa3) {
; #pragma unroll
;   for (int r = 0; r < 16; ++r) p1[r] = __builtin_amdgcn_exp2f(p1[r]);
;   float ps = 0;
; #pragma unroll
;   for (int r = 0; r < 16; ++r) ps += p0[r];
; #pragma unroll
;   for (int r = 0; r < 16; ++r) ps += p1[r];
;   { auto rr = __builtin_amdgcn_permlane32_swap(__float_as_uint(ps), __float_as_uint(ps), false, false);
;     ps = __uint_as_float(rr[0]) + __uint_as_float(rr[1]); }
;   l_reg += ps;
;     ...
;   PK4(p0, 0, pa0); PK4(p0, 8, pa1); PK4(p1, 0, pa2); PK4(p1, 8, pa3);
; __device__ __forceinline__ void qkt(f32x16& p0, f32x16& p1, const char* Ks, const bf16x8* qr, int r32, int hi, float negM) {
; #pragma unroll
;   for (int r = 0; r < 16; ++r) { p0[r] = negM; p1[r] = negM; }
;   __builtin_amdgcn_s_setprio(1);
;   const char* kn = Ks + r32 * 256; const int xn = r32 & 15;
; #pragma unroll
;   for (int d0 = 0; d0 < 8; ++d0) { const int off = ((d0 * 2 + hi) ^ xn) << 4;
;     bf16x8 b0 = *reinterpret_cast<const bf16x8*>(kn + off);
;     bf16x8 b1 = *reinterpret_cast<const bf16x8*>(kn + 32 * 256 + off);
;     p0 = __builtin_amdgcn_mfma_f32_32x32x16_bf16(b0, qr[d0], p0, 0, 0, 0);
;     p1 = __builtin_amdgcn_mfma_f32_32x32x16_bf16(b1, qr[d0], p1, 0, 0, 0); }
;   const char* kr = Ks + KROPE_OFF + r32 * 128; const int xr = (r32 >> 1) & 7;
; #pragma unroll
;   for (int d0 = 8; d0 < 12; ++d0) { const int off = (((d0 - 8) * 2 + hi) ^ xr) << 4;
;     bf16x8 b0 = *reinterpret_cast<const bf16x8*>(kr + off);
;     bf16x8 b1 = *reinterpret_cast<const bf16x8*>(kr + 32 * 128 + off);
;     p0 = __builtin_amdgcn_mfma_f32_32x32x16_bf16(b0, qr[d0], p0, 0, 0, 0);
;     p1 = __builtin_amdgcn_mfma_f32_32x32x16_bf16(b1, qr[d0], p1, 0, 0, 0); }
;   __builtin_amdgcn_s_setprio(0);
; }
	s_setprio 1
	v_or_b32_e32 v179, 0xe000, v213
	v_add_u32_e32 v96, v213, v214
	v_add_u32_e32 v100, v179, v214
	ds_read_b128 v[96:99], v96 offset:57344
	ds_read_b128 v[180:183], v100 offset:8192
	s_waitcnt lgkmcnt(0)
	v_mfma_f32_32x32x16_bf16 v[112:127], v[96:99], v[128:131], v[0:15]
	v_mfma_f32_32x32x16_bf16 v[96:111], v[180:183], v[128:131], v[0:15]
	v_add_u32_e32 v128, v213, v215
	v_add_u32_e32 v180, v179, v215
	ds_read_b128 v[128:131], v128 offset:57344
	ds_read_b128 v[180:183], v180 offset:8192
	s_waitcnt lgkmcnt(0)
	v_mfma_f32_32x32x16_bf16 v[112:127], v[128:131], v[132:135], v[112:127]
	v_add_u32_e32 v128, v213, v216
	ds_read_b128 v[128:131], v128 offset:57344
	v_mfma_f32_32x32x16_bf16 v[96:111], v[180:183], v[132:135], v[96:111]
	v_add_u32_e32 v132, v179, v216
	ds_read_b128 v[132:135], v132 offset:8192
	s_waitcnt lgkmcnt(0)
	v_mfma_f32_32x32x16_bf16 v[112:127], v[128:131], v[136:139], v[112:127]
	v_add_u32_e32 v128, v213, v217
	ds_read_b128 v[128:131], v128 offset:57344
	v_mfma_f32_32x32x16_bf16 v[96:111], v[132:135], v[136:139], v[96:111]
	v_add_u32_e32 v132, v179, v217
	ds_read_b128 v[132:135], v132 offset:8192
	v_or_b32_e32 v136, 0x12000, v222
	s_waitcnt lgkmcnt(0)
	v_mfma_f32_32x32x16_bf16 v[112:127], v[128:131], v[140:143], v[112:127]
	v_add_u32_e32 v128, v213, v218
	ds_read_b128 v[128:131], v128 offset:57344
	v_mfma_f32_32x32x16_bf16 v[96:111], v[132:135], v[140:143], v[96:111]
	v_add_u32_e32 v132, v179, v218
	ds_read_b128 v[132:135], v132 offset:8192
	s_waitcnt lgkmcnt(0)
	v_mfma_f32_32x32x16_bf16 v[112:127], v[128:131], v[144:147], v[112:127]
	v_add_u32_e32 v128, v213, v219
	ds_read_b128 v[128:131], v128 offset:57344
	v_mfma_f32_32x32x16_bf16 v[96:111], v[132:135], v[144:147], v[96:111]
	v_add_u32_e32 v132, v179, v219
	ds_read_b128 v[132:135], v132 offset:8192
	s_waitcnt lgkmcnt(0)
	v_mfma_f32_32x32x16_bf16 v[112:127], v[128:131], v[148:151], v[112:127]
	v_add_u32_e32 v128, v213, v220
	ds_read_b128 v[128:131], v128 offset:57344
	v_mfma_f32_32x32x16_bf16 v[96:111], v[132:135], v[148:151], v[96:111]
	v_add_u32_e32 v132, v179, v220
	ds_read_b128 v[132:135], v132 offset:8192
	s_waitcnt lgkmcnt(0)
	v_mfma_f32_32x32x16_bf16 v[112:127], v[128:131], v[152:155], v[112:127]
	v_add_u32_e32 v128, v213, v221
	ds_read_b128 v[128:131], v128 offset:57344
	v_mfma_f32_32x32x16_bf16 v[96:111], v[132:135], v[152:155], v[96:111]
	v_add_u32_e32 v132, v179, v221
	ds_read_b128 v[132:135], v132 offset:8192
	s_waitcnt lgkmcnt(0)
	v_mfma_f32_32x32x16_bf16 v[112:127], v[128:131], v[156:159], v[112:127]
	v_mfma_f32_32x32x16_bf16 v[96:111], v[132:135], v[156:159], v[96:111]
	v_add_u32_e32 v132, v136, v223
	ds_read_b128 v[128:131], v132
	ds_read_b128 v[132:135], v132 offset:4096
	s_waitcnt lgkmcnt(0)
	v_mfma_f32_32x32x16_bf16 v[112:127], v[128:131], v[164:167], v[112:127]
	v_mfma_f32_32x32x16_bf16 v[96:111], v[132:135], v[164:167], v[96:111]
	v_add_u32_e32 v132, v136, v224
	ds_read_b128 v[128:131], v132
	ds_read_b128 v[132:135], v132 offset:4096
	s_waitcnt lgkmcnt(0)
	v_mfma_f32_32x32x16_bf16 v[112:127], v[128:131], v[172:175], v[112:127]
	v_mfma_f32_32x32x16_bf16 v[96:111], v[132:135], v[172:175], v[96:111]
	v_add_u32_e32 v132, v136, v225
	ds_read_b128 v[128:131], v132
	ds_read_b128 v[132:135], v132 offset:4096
	s_waitcnt lgkmcnt(0)
	v_mfma_f32_32x32x16_bf16 v[112:127], v[128:131], v[160:163], v[112:127]
	v_mfma_f32_32x32x16_bf16 v[96:111], v[132:135], v[160:163], v[96:111]
	v_add_u32_e32 v132, v136, v226
	ds_read_b128 v[128:131], v132
	ds_read_b128 v[132:135], v132 offset:4096
	s_waitcnt lgkmcnt(0)
	v_mfma_f32_32x32x16_bf16 v[112:127], v[128:131], v[168:171], v[112:127]
	v_mfma_f32_32x32x16_bf16 v[96:111], v[132:135], v[168:171], v[96:111]
	s_setprio 0
	v_exp_f32_e32 v128, v80
	v_add_f32_e32 v80, 0, v240
	v_add_f32_e32 v80, v242, v80
	v_add_f32_e32 v80, v238, v80
	v_add_f32_e32 v80, v241, v80
	v_add_f32_e32 v80, v236, v80
	v_add_f32_e32 v80, v239, v80
	v_add_f32_e32 v80, v235, v80
	v_add_f32_e32 v80, v237, v80
	v_add_f32_e32 v80, v232, v80
	v_add_f32_e32 v80, v234, v80
	v_add_f32_e32 v80, v230, v80
	v_add_f32_e32 v80, v233, v80
	v_add_f32_e32 v80, v228, v80
	v_exp_f32_e32 v81, v81
	v_add_f32_e32 v80, v231, v80
	v_exp_f32_e32 v129, v82
	v_add_f32_e32 v80, v227, v80
	v_exp_f32_e32 v83, v83
	v_add_f32_e32 v80, v229, v80
	v_exp_f32_e32 v130, v84
	v_add_f32_e32 v80, v128, v80
	v_exp_f32_e32 v131, v85
	v_add_f32_e32 v80, v81, v80
	v_exp_f32_e32 v132, v86
	v_add_f32_e32 v80, v129, v80
	v_exp_f32_e32 v133, v87
	v_add_f32_e32 v80, v83, v80
	v_exp_f32_e32 v134, v88
	v_add_f32_e32 v80, v130, v80
	v_exp_f32_e32 v135, v89
	v_add_f32_e32 v80, v131, v80
	v_exp_f32_e32 v136, v90
	v_add_f32_e32 v80, v132, v80
	v_exp_f32_e32 v137, v91
	v_add_f32_e32 v80, v133, v80
	v_exp_f32_e32 v138, v92
	v_add_f32_e32 v80, v134, v80
	v_exp_f32_e32 v139, v93
	v_add_f32_e32 v80, v135, v80
	v_exp_f32_e32 v140, v94
	v_add_f32_e32 v80, v136, v80
	v_exp_f32_e32 v141, v95
	v_add_f32_e32 v80, v137, v80
	v_add_f32_e32 v80, v138, v80
	v_add_f32_e32 v80, v139, v80
	v_add_f32_e32 v80, v140, v80
	v_add_f32_e32 v80, v141, v80
	v_mov_b32_e32 v82, v80
	s_nop 1
	v_permlane32_swap_b32_e32 v80, v82
	s_nop 0
	v_cvt_pk_bf16_f32 v84, v240, v242
	s_nop 0
	v_cvt_pk_bf16_f32 v85, v238, v241
	s_nop 0
	v_cvt_pk_bf16_f32 v86, v236, v239
	s_nop 0
	v_cvt_pk_bf16_f32 v87, v235, v237
	s_nop 0
	v_cvt_pk_bf16_f32 v88, v232, v234
	s_nop 0
	v_cvt_pk_bf16_f32 v89, v230, v233
	s_nop 0
	v_cvt_pk_bf16_f32 v90, v228, v231
	s_nop 0
	v_cvt_pk_bf16_f32 v91, v227, v229
	s_nop 0
	v_cvt_pk_bf16_f32 v92, v128, v81
	s_nop 0
	v_cvt_pk_bf16_f32 v93, v129, v83
	s_nop 0
	v_cvt_pk_bf16_f32 v94, v130, v131
	s_nop 0
	v_cvt_pk_bf16_f32 v95, v132, v133
	s_nop 0
	v_cvt_pk_bf16_f32 v128, v134, v135
	s_nop 0
	v_cvt_pk_bf16_f32 v129, v136, v137
	s_nop 0
	v_cvt_pk_bf16_f32 v130, v138, v139
	s_nop 0
	v_cvt_pk_bf16_f32 v131, v140, v141
	s_nop 0
	v_permlane32_swap_b32_e32 v84, v86
	v_permlane32_swap_b32_e32 v85, v87
	v_permlane32_swap_b32_e32 v88, v90
	v_permlane32_swap_b32_e32 v89, v91
	v_permlane32_swap_b32_e32 v92, v94
	v_permlane32_swap_b32_e32 v93, v95
	v_permlane32_swap_b32_e32 v128, v130
	v_permlane32_swap_b32_e32 v129, v131
	ds_read_b64_tr_b16 v[132:133], v212 offset:0
	ds_read_b64_tr_b16 v[134:135], v212 offset:0x800
	ds_read_b64_tr_b16 v[136:137], v212 offset:0x1000
	ds_read_b64_tr_b16 v[138:139], v212 offset:0x1800
	ds_read_b64_tr_b16 v[140:141], v212 offset:0x2000
	ds_read_b64_tr_b16 v[142:143], v212 offset:0x2800
	ds_read_b64_tr_b16 v[144:145], v212 offset:0x3000
	ds_read_b64_tr_b16 v[146:147], v212 offset:0x3800
	s_waitcnt lgkmcnt(0)
; #define SBAR() __builtin_amdgcn_sched_barrier(0)
; __device__ __forceinline__ void finishSM(f32x16& p0, f32x16& p1, float& l_reg, bf16x8& pa0, bf16x8& pa1, bf16x8& pa2, bf16x8& pa3) {
; #pragma unroll
;   for (int r = 0; r < 16; ++r) p1[r] = __builtin_amdgcn_exp2f(p1[r]);
;   float ps = 0;
; #pragma unroll
;   for (int r = 0; r < 16; ++r) ps += p0[r];
; #pragma unroll
;   for (int r = 0; r < 16; ++r) ps += p1[r];
;   { auto rr = __builtin_amdgcn_permlane32_swap(__float_as_uint(ps), __float_as_uint(ps), false, false);
;     ps = __uint_as_float(rr[0]) + __uint_as_float(rr[1]); }
;   l_reg += ps;
;     ...
;   PK4(p0, 0, pa0); PK4(p0, 8, pa1); PK4(p1, 0, pa2); PK4(p1, 8, pa3);
; template <int OFF> __device__ __forceinline__ s16x4 tr_read(int vb) {
;   s16x4 r; asm volatile("ds_read_b64_tr_b16 %0, %1 offset:%2" : "=&v"(r) : "v"(vb), "i"(OFF) : "memory"); return r;
; }
; template <int D0> __device__ __forceinline__ void pv_one(f32x16& od, int vb, bf16x8 pa0, bf16x8 pa1, bf16x8 pa2, bf16x8 pa3) {
;   const s16x4 l0 = tr_read<v_rd_off(D0, 0, 0)>(vb), h0 = tr_read<v_rd_off(D0, 0, 1)>(vb), l1 = tr_read<v_rd_off(D0, 1, 0)>(vb), h1 = tr_read<v_rd_off(D0, 1, 1)>(vb);
;   const s16x4 l2 = tr_read<v_rd_off(D0, 2, 0)>(vb), h2 = tr_read<v_rd_off(D0, 2, 1)>(vb), l3 = tr_read<v_rd_off(D0, 3, 0)>(vb), h3 = tr_read<v_rd_off(D0, 3, 1)>(vb);
;   asm volatile("s_waitcnt lgkmcnt(0)" ::: "memory"); SBAR();
;     ...
;   od = __builtin_amdgcn_mfma_f32_32x32x16_bf16(pa0, PK(l0, h0), od, 0, 0, 0);
;   od = __builtin_amdgcn_mfma_f32_32x32x16_bf16(pa1, PK(l1, h1), od, 0, 0, 0);
;   od = __builtin_amdgcn_mfma_f32_32x32x16_bf16(pa2, PK(l2, h2), od, 0, 0, 0);
;   od = __builtin_amdgcn_mfma_f32_32x32x16_bf16(pa3, PK(l3, h3), od, 0, 0, 0);
;     ...
; }
; __device__ __forceinline__ void pv_d0(f32x16* o, int vb, bf16x8 pa0, bf16x8 pa1, bf16x8 pa2, bf16x8 pa3) {
;   pv_one<0>(o[0], vb, pa0, pa1, pa2, pa3); pv_one<1>(o[1], vb, pa0, pa1, pa2, pa3); pv_one<2>(o[2], vb, pa0, pa1, pa2, pa3); pv_one<3>(o[3], vb, pa0, pa1, pa2, pa3);
	s_nop 0
	v_mfma_f32_32x32x16_bf16 v[64:79], v[84:87], v[132:135], v[64:79]
	ds_read_b64_tr_b16 v[132:133], v212 offset:0x200
	ds_read_b64_tr_b16 v[134:135], v212 offset:0xa00
	v_mfma_f32_32x32x16_bf16 v[64:79], v[88:91], v[136:139], v[64:79]
	ds_read_b64_tr_b16 v[136:137], v212 offset:0x1200
	ds_read_b64_tr_b16 v[138:139], v212 offset:0x1a00
	v_mfma_f32_32x32x16_bf16 v[64:79], v[92:95], v[140:143], v[64:79]
	ds_read_b64_tr_b16 v[140:141], v212 offset:0x2200
	ds_read_b64_tr_b16 v[142:143], v212 offset:0x2a00
	ds_read_b64_tr_b16 v[148:149], v212 offset:0x3200
	ds_read_b64_tr_b16 v[150:151], v212 offset:0x3a00
	s_waitcnt lgkmcnt(0)
	v_mfma_f32_32x32x16_bf16 v[64:79], v[128:131], v[144:147], v[64:79]
	v_mfma_f32_32x32x16_bf16 v[48:63], v[84:87], v[132:135], v[48:63]
	ds_read_b64_tr_b16 v[132:133], v212 offset:0x400
	ds_read_b64_tr_b16 v[134:135], v212 offset:0xc00
	v_mfma_f32_32x32x16_bf16 v[48:63], v[88:91], v[136:139], v[48:63]
	ds_read_b64_tr_b16 v[136:137], v212 offset:0x1400
	ds_read_b64_tr_b16 v[138:139], v212 offset:0x1c00
	v_mfma_f32_32x32x16_bf16 v[48:63], v[92:95], v[140:143], v[48:63]
	ds_read_b64_tr_b16 v[140:141], v212 offset:0x2400
	ds_read_b64_tr_b16 v[142:143], v212 offset:0x2c00
	ds_read_b64_tr_b16 v[144:145], v212 offset:0x3400
	ds_read_b64_tr_b16 v[146:147], v212 offset:0x3c00
	s_waitcnt lgkmcnt(0)
	v_mfma_f32_32x32x16_bf16 v[48:63], v[128:131], v[148:151], v[48:63]
	v_mfma_f32_32x32x16_bf16 v[32:47], v[84:87], v[132:135], v[32:47]
	ds_read_b64_tr_b16 v[132:133], v212 offset:0x600
	ds_read_b64_tr_b16 v[134:135], v212 offset:0xe00
	v_mfma_f32_32x32x16_bf16 v[32:47], v[88:91], v[136:139], v[32:47]
	ds_read_b64_tr_b16 v[136:137], v212 offset:0x1600
	ds_read_b64_tr_b16 v[138:139], v212 offset:0x1e00
	v_mfma_f32_32x32x16_bf16 v[32:47], v[92:95], v[140:143], v[32:47]
	ds_read_b64_tr_b16 v[140:141], v212 offset:0x2600
	ds_read_b64_tr_b16 v[142:143], v212 offset:0x2e00
	ds_read_b64_tr_b16 v[148:149], v212 offset:0x3600
	ds_read_b64_tr_b16 v[150:151], v212 offset:0x3e00
	s_waitcnt lgkmcnt(0)
	v_mfma_f32_32x32x16_bf16 v[32:47], v[128:131], v[144:147], v[32:47]
	v_exp_f32_e32 v112, v112
	v_exp_f32_e32 v113, v113
	v_exp_f32_e32 v114, v114
	v_exp_f32_e32 v115, v115
	v_exp_f32_e32 v116, v116
	v_mfma_f32_32x32x16_bf16 v[16:31], v[84:87], v[132:135], v[16:31]
	v_add_f32_e32 v81, 0, v112
	v_exp_f32_e32 v117, v117
	v_add_f32_e32 v81, v113, v81
	v_exp_f32_e32 v87, v118
	v_add_f32_e32 v81, v114, v81
	v_exp_f32_e32 v118, v119
	v_add_f32_e32 v81, v115, v81
	v_exp_f32_e32 v119, v120
	v_add_f32_e32 v81, v116, v81
	v_exp_f32_e32 v120, v121
	v_add_f32_e32 v81, v117, v81
	v_exp_f32_e32 v121, v122
	v_add_f32_e32 v81, v87, v81
	v_exp_f32_e32 v122, v123
	v_add_f32_e32 v81, v118, v81
	v_exp_f32_e32 v123, v124
	v_mfma_f32_32x32x16_bf16 v[16:31], v[88:91], v[136:139], v[16:31]
	v_add_f32_e32 v81, v119, v81
	v_exp_f32_e32 v90, v125
	v_add_f32_e32 v81, v120, v81
	v_exp_f32_e32 v91, v126
	v_add_f32_e32 v81, v121, v81
	v_exp_f32_e32 v124, v127
	v_add_f32_e32 v81, v122, v81
	v_exp_f32_e32 v96, v96
	v_add_f32_e32 v81, v123, v81
	v_exp_f32_e32 v97, v97
	v_add_f32_e32 v81, v90, v81
	v_exp_f32_e32 v98, v98
	v_add_f32_e32 v81, v91, v81
	v_exp_f32_e32 v99, v99
	v_add_f32_e32 v81, v124, v81
	v_mfma_f32_32x32x16_bf16 v[16:31], v[92:95], v[140:143], v[16:31]
	v_exp_f32_e32 v94, v100
	v_add_f32_e32 v81, v96, v81
	v_exp_f32_e32 v95, v101
	v_add_f32_e32 v81, v97, v81
	v_exp_f32_e32 v100, v102
	v_add_f32_e32 v81, v98, v81
	v_exp_f32_e32 v101, v103
	v_add_f32_e32 v81, v99, v81
	v_exp_f32_e32 v102, v104
	v_add_f32_e32 v81, v94, v81
	v_exp_f32_e32 v103, v105
	v_add_f32_e32 v81, v95, v81
	v_exp_f32_e32 v104, v106
	v_add_f32_e32 v81, v100, v81
	v_exp_f32_e32 v105, v107
	v_add_f32_e32 v81, v101, v81
	v_exp_f32_e32 v106, v108
	v_add_f32_e32 v81, v102, v81
	v_exp_f32_e32 v107, v109
	v_add_f32_e32 v81, v103, v81
	v_mfma_f32_32x32x16_bf16 v[16:31], v[128:131], v[148:151], v[16:31]
	v_exp_f32_e32 v108, v110
	v_add_f32_e32 v81, v104, v81
	v_exp_f32_e32 v109, v111
	v_add_f32_e32 v81, v105, v81
	v_add_f32_e32 v81, v106, v81
	v_add_f32_e32 v81, v107, v81
	v_add_f32_e32 v81, v108, v81
	v_add_f32_e32 v81, v109, v81
	v_mov_b32_e32 v83, v81
	s_nop 1
	v_permlane32_swap_b32_e32 v81, v83
	s_nop 0
	v_cvt_pk_bf16_f32 v84, v112, v113
	s_nop 0
	v_cvt_pk_bf16_f32 v85, v114, v115
	s_nop 0
	v_cvt_pk_bf16_f32 v86, v116, v117
	s_nop 0
	v_cvt_pk_bf16_f32 v87, v87, v118
	s_nop 0
	v_cvt_pk_bf16_f32 v88, v119, v120
	s_nop 0
	v_cvt_pk_bf16_f32 v89, v121, v122
	s_nop 0
	v_cvt_pk_bf16_f32 v90, v123, v90
	s_nop 0
	v_cvt_pk_bf16_f32 v91, v91, v124
	s_nop 0
	v_cvt_pk_bf16_f32 v92, v96, v97
	s_nop 0
	v_cvt_pk_bf16_f32 v93, v98, v99
	s_nop 0
	v_cvt_pk_bf16_f32 v94, v94, v95
	s_nop 0
	v_cvt_pk_bf16_f32 v95, v100, v101
	s_nop 0
	v_cvt_pk_bf16_f32 v96, v102, v103
	s_nop 0
	v_cvt_pk_bf16_f32 v97, v104, v105
	s_nop 0
	v_cvt_pk_bf16_f32 v98, v106, v107
	s_nop 0
	v_cvt_pk_bf16_f32 v99, v108, v109
	s_nop 0
	v_permlane32_swap_b32_e32 v84, v86
	v_permlane32_swap_b32_e32 v85, v87
	v_permlane32_swap_b32_e32 v88, v90
	v_permlane32_swap_b32_e32 v89, v91
	v_permlane32_swap_b32_e32 v92, v94
	v_permlane32_swap_b32_e32 v93, v95
	v_permlane32_swap_b32_e32 v96, v98
	v_permlane32_swap_b32_e32 v97, v99
	v_or_b32_e32 v120, 0xa000, v212
	ds_read_b64_tr_b16 v[100:101], v120 offset:0
	ds_read_b64_tr_b16 v[102:103], v120 offset:0x800
	ds_read_b64_tr_b16 v[104:105], v120 offset:0x1000
	ds_read_b64_tr_b16 v[106:107], v120 offset:0x1800
	ds_read_b64_tr_b16 v[108:109], v120 offset:0x2000
	ds_read_b64_tr_b16 v[110:111], v120 offset:0x2800
	ds_read_b64_tr_b16 v[112:113], v120 offset:0x3000
	ds_read_b64_tr_b16 v[114:115], v120 offset:0x3800
	s_waitcnt lgkmcnt(0)
; #define SBAR() __builtin_amdgcn_sched_barrier(0)
; template <int D0> __device__ __forceinline__ void pv_one(f32x16& od, int vb, bf16x8 pa0, bf16x8 pa1, bf16x8 pa2, bf16x8 pa3) {
;   const s16x4 l0 = tr_read<v_rd_off(D0, 0, 0)>(vb), h0 = tr_read<v_rd_off(D0, 0, 1)>(vb), l1 = tr_read<v_rd_off(D0, 1, 0)>(vb), h1 = tr_read<v_rd_off(D0, 1, 1)>(vb);
;   const s16x4 l2 = tr_read<v_rd_off(D0, 2, 0)>(vb), h2 = tr_read<v_rd_off(D0, 2, 1)>(vb), l3 = tr_read<v_rd_off(D0, 3, 0)>(vb), h3 = tr_read<v_rd_off(D0, 3, 1)>(vb);
;   asm volatile("s_waitcnt lgkmcnt(0)" ::: "memory"); SBAR();
;     ...
;   od = __builtin_amdgcn_mfma_f32_32x32x16_bf16(pa0, PK(l0, h0), od, 0, 0, 0);
;   od = __builtin_amdgcn_mfma_f32_32x32x16_bf16(pa1, PK(l1, h1), od, 0, 0, 0);
;   od = __builtin_amdgcn_mfma_f32_32x32x16_bf16(pa2, PK(l2, h2), od, 0, 0, 0);
;   od = __builtin_amdgcn_mfma_f32_32x32x16_bf16(pa3, PK(l3, h3), od, 0, 0, 0);
;     ...
; }
; __device__ __forceinline__ void pv_d0(f32x16* o, int vb, bf16x8 pa0, bf16x8 pa1, bf16x8 pa2, bf16x8 pa3) {
;   pv_one<0>(o[0], vb, pa0, pa1, pa2, pa3); pv_one<1>(o[1], vb, pa0, pa1, pa2, pa3); pv_one<2>(o[2], vb, pa0, pa1, pa2, pa3); pv_one<3>(o[3], vb, pa0, pa1, pa2, pa3);
; __device__ __forceinline__ void attn_body(const u16* __restrict__ Qb, const u16* __restrict__ Kn, const u16* __restrict__ Kr,
;                                           u16* __restrict__ Ob, char* lds, int tid, const float* __restrict__ gq_, const float* __restrict__ tab_, int qpos0, float negM) {
;     ...
;   pv_d0(o, vrb + cur, pa0, pa1, pa2, pa3);
;   if (hi == 0) li_l[r32] = l_reg; asm volatile("s_waitcnt lgkmcnt(0)" ::: "memory");
	s_nop 0
	v_mfma_f32_32x32x16_bf16 v[64:79], v[84:87], v[100:103], v[64:79]
	ds_read_b64_tr_b16 v[100:101], v120 offset:0x200
	ds_read_b64_tr_b16 v[102:103], v120 offset:0xa00
	v_mfma_f32_32x32x16_bf16 v[64:79], v[88:91], v[104:107], v[64:79]
	ds_read_b64_tr_b16 v[104:105], v120 offset:0x1200
	ds_read_b64_tr_b16 v[106:107], v120 offset:0x1a00
	v_mfma_f32_32x32x16_bf16 v[64:79], v[92:95], v[108:111], v[64:79]
	ds_read_b64_tr_b16 v[108:109], v120 offset:0x2200
	ds_read_b64_tr_b16 v[110:111], v120 offset:0x2a00
	ds_read_b64_tr_b16 v[116:117], v120 offset:0x3200
	ds_read_b64_tr_b16 v[118:119], v120 offset:0x3a00
	s_waitcnt lgkmcnt(0)
	v_mfma_f32_32x32x16_bf16 v[64:79], v[96:99], v[112:115], v[64:79]
	v_mfma_f32_32x32x16_bf16 v[48:63], v[84:87], v[100:103], v[48:63]
	ds_read_b64_tr_b16 v[100:101], v120 offset:0x400
	ds_read_b64_tr_b16 v[102:103], v120 offset:0xc00
	v_mfma_f32_32x32x16_bf16 v[48:63], v[88:91], v[104:107], v[48:63]
	ds_read_b64_tr_b16 v[104:105], v120 offset:0x1400
	ds_read_b64_tr_b16 v[106:107], v120 offset:0x1c00
	v_mfma_f32_32x32x16_bf16 v[48:63], v[92:95], v[108:111], v[48:63]
	ds_read_b64_tr_b16 v[108:109], v120 offset:0x2400
	ds_read_b64_tr_b16 v[110:111], v120 offset:0x2c00
	ds_read_b64_tr_b16 v[112:113], v120 offset:0x3400
	ds_read_b64_tr_b16 v[114:115], v120 offset:0x3c00
	s_waitcnt lgkmcnt(0)
	v_mfma_f32_32x32x16_bf16 v[48:63], v[96:99], v[116:119], v[48:63]
	v_mfma_f32_32x32x16_bf16 v[32:47], v[84:87], v[100:103], v[32:47]
	ds_read_b64_tr_b16 v[100:101], v120 offset:0x600
	ds_read_b64_tr_b16 v[102:103], v120 offset:0xe00
	v_mfma_f32_32x32x16_bf16 v[32:47], v[88:91], v[104:107], v[32:47]
	ds_read_b64_tr_b16 v[104:105], v120 offset:0x1600
	ds_read_b64_tr_b16 v[106:107], v120 offset:0x1e00
	v_mfma_f32_32x32x16_bf16 v[32:47], v[92:95], v[108:111], v[32:47]
	ds_read_b64_tr_b16 v[108:109], v120 offset:0x2600
	ds_read_b64_tr_b16 v[110:111], v120 offset:0x2e00
	ds_read_b64_tr_b16 v[116:117], v120 offset:0x3600
	ds_read_b64_tr_b16 v[118:119], v120 offset:0x3e00
	s_waitcnt lgkmcnt(0)
	v_mfma_f32_32x32x16_bf16 v[32:47], v[96:99], v[112:115], v[32:47]
	v_mfma_f32_32x32x16_bf16 v[16:31], v[84:87], v[100:103], v[16:31]
	v_cmp_gt_u32_e32 vcc, 32, v209
	v_mfma_f32_32x32x16_bf16 v[16:31], v[88:91], v[104:107], v[16:31]
	v_mfma_f32_32x32x16_bf16 v[16:31], v[92:95], v[108:111], v[16:31]
	v_mfma_f32_32x32x16_bf16 v[16:31], v[96:99], v[116:119], v[16:31]
	s_and_saveexec_b64 s[48:49], vcc
	s_cbranch_execz .LBB0_717
	v_pk_add_f32 v[80:81], v[80:81], v[82:83]
	v_lshl_add_u32 v84, v206, 2, v178
	v_add_f32_e32 v80, v176, v80
	v_add_f32_e32 v80, v80, v81
	ds_write_b32 v84, v80
	s_branch .LBB0_717
